# nt hint on the P2b producer row loads and on the P5 out_pre loads (both last-use streams), on top of sc1 out_pre stores
# speedup vs baseline: 1.0100x; 1.0100x over previous
.LBB0_188:
	s_mul_i32 s28, s3, 0x1200
	v_add_u32_e32 v136, s28, v132
	v_lshl_add_u64 v[40:41], v[136:137], 1, s[26:27]
	v_add_u32_e32 v42, 0x1200, v136
	v_mov_b32_e32 v43, v137
	v_lshl_add_u64 v[42:43], v[42:43], 1, s[26:27]
	global_load_dwordx4 v[68:71], v[40:41], off nt
	global_load_dwordx4 v[64:67], v[42:43], off nt
	v_add_u32_e32 v40, 0x2400, v136
	v_mov_b32_e32 v41, v137
	v_lshl_add_u64 v[40:41], v[40:41], 1, s[26:27]
	v_add_u32_e32 v42, 0x3600, v136
	v_mov_b32_e32 v43, v137
	v_lshl_add_u64 v[42:43], v[42:43], 1, s[26:27]
	global_load_dwordx4 v[60:63], v[40:41], off nt
	global_load_dwordx4 v[56:59], v[42:43], off nt
	v_add_u32_e32 v40, 0x4800, v136
	v_mov_b32_e32 v41, v137
	v_lshl_add_u64 v[40:41], v[40:41], 1, s[26:27]
	v_add_u32_e32 v42, 0x5a00, v136
	v_mov_b32_e32 v43, v137
	v_lshl_add_u64 v[42:43], v[42:43], 1, s[26:27]
	global_load_dwordx4 v[52:55], v[40:41], off nt
	global_load_dwordx4 v[48:51], v[42:43], off nt
	v_add_u32_e32 v40, 0x6c00, v136
	v_mov_b32_e32 v41, v137
	v_add_u32_e32 v136, 0x7e00, v136
	v_lshl_add_u64 v[40:41], v[40:41], 1, s[26:27]
	v_lshl_add_u64 v[42:43], v[136:137], 1, s[26:27]
	global_load_dwordx4 v[44:47], v[40:41], off nt
	s_nop 0
	global_load_dwordx4 v[40:43], v[42:43], off nt
	s_and_b64 vcc, exec, s[76:77]
	s_cbranch_vccnz .Lp2b_hist_done
	s_waitcnt vmcnt(8)
	v_lshlrev_b32_e32 v108, 16, v208
	v_and_b32_e32 v109, 0xffff0000, v208
	v_lshlrev_b32_e32 v110, 16, v209
	v_and_b32_e32 v111, 0xffff0000, v209
	v_lshlrev_b32_e32 v104, 16, v210
	v_and_b32_e32 v105, 0xffff0000, v210
	v_lshlrev_b32_e32 v106, 16, v211
	v_and_b32_e32 v107, 0xffff0000, v211
	v_lshlrev_b32_e32 v120, 16, v212
	v_and_b32_e32 v121, 0xffff0000, v212
	v_lshlrev_b32_e32 v122, 16, v213
	v_and_b32_e32 v123, 0xffff0000, v213
	v_lshlrev_b32_e32 v124, 16, v214
	v_and_b32_e32 v125, 0xffff0000, v214
	v_lshlrev_b32_e32 v126, 16, v215
	v_and_b32_e32 v127, 0xffff0000, v215
	v_lshlrev_b32_e32 v116, 16, v216
	v_and_b32_e32 v117, 0xffff0000, v216
	v_lshlrev_b32_e32 v118, 16, v217
	v_and_b32_e32 v119, 0xffff0000, v217
	v_lshlrev_b32_e32 v112, 16, v218
	v_and_b32_e32 v113, 0xffff0000, v218
	v_lshlrev_b32_e32 v114, 16, v219
	v_and_b32_e32 v115, 0xffff0000, v219

.LBB0_190:
	v_add_u32_e32 v136, 0xfffdd200, v168
	v_lshl_add_u64 v[72:73], v[136:137], 1, s[26:27]
	v_add_u32_e32 v136, 0xfffde400, v168
	v_lshl_add_u64 v[74:75], v[136:137], 1, s[26:27]
	v_add_u32_e32 v136, 0xfffdf600, v168
	s_waitcnt lgkmcnt(0)
	s_barrier
	global_load_dwordx4 v[100:103], v[72:73], off nt
	global_load_dwordx4 v[96:99], v[74:75], off nt
	v_lshl_add_u64 v[72:73], v[136:137], 1, s[26:27]
	v_add_u32_e32 v136, 0xfffe0800, v168
	v_lshl_add_u64 v[74:75], v[136:137], 1, s[26:27]
	v_add_u32_e32 v136, 0xfffe1a00, v168
	global_load_dwordx4 v[92:95], v[72:73], off nt
	global_load_dwordx4 v[88:91], v[74:75], off nt
	v_lshl_add_u64 v[72:73], v[136:137], 1, s[26:27]
	v_add_u32_e32 v136, 0xfffe2c00, v168
	v_lshl_add_u64 v[74:75], v[136:137], 1, s[26:27]
	v_add_u32_e32 v136, 0xfffe3e00, v168
	global_load_dwordx4 v[84:87], v[72:73], off nt
	global_load_dwordx4 v[80:83], v[74:75], off nt
	v_lshl_add_u64 v[72:73], v[136:137], 1, s[26:27]
	v_add_u32_e32 v136, 0xfffe5000, v168
	v_lshl_add_u64 v[74:75], v[136:137], 1, s[26:27]
	global_load_dwordx4 v[76:79], v[72:73], off nt
	s_nop 0
	global_load_dwordx4 v[72:75], v[74:75], off nt
	s_waitcnt vmcnt(16)
	v_pk_fma_f32 v[108:109], v[4:5], v[108:109], v[36:37]
	s_waitcnt vmcnt(15)
	v_lshlrev_b32_e32 v172, 16, v68
	v_pk_fma_f32 v[108:109], v[12:13], v[120:121], v[108:109]
	v_and_b32_e32 v173, 0xffff0000, v68
	v_pk_fma_f32 v[108:109], v[20:21], v[116:117], v[108:109]
	s_and_b32 s90, s88, 0x4000
	v_pk_fma_f32 v[178:179], v[28:29], v[172:173], v[108:109]
	v_lshlrev_b32_e32 v108, 16, v69
	v_and_b32_e32 v109, 0xffff0000, v69
	v_pk_fma_f32 v[68:69], v[6:7], v[110:111], v[38:39]
	v_lshlrev_b32_e32 v110, 16, v70
	v_pk_fma_f32 v[68:69], v[14:15], v[122:123], v[68:69]
	v_and_b32_e32 v111, 0xffff0000, v70
	v_pk_fma_f32 v[68:69], v[22:23], v[118:119], v[68:69]
	s_nop 0
	v_pk_fma_f32 v[176:177], v[30:31], v[108:109], v[68:69]
	v_pk_fma_f32 v[68:69], v[0:1], v[104:105], v[32:33]
	v_lshlrev_b32_e32 v104, 16, v71
	v_pk_fma_f32 v[68:69], v[8:9], v[124:125], v[68:69]
	v_and_b32_e32 v105, 0xffff0000, v71
	v_pk_fma_f32 v[68:69], v[16:17], v[112:113], v[68:69]
	s_nop 0
	v_pk_fma_f32 v[174:175], v[24:25], v[110:111], v[68:69]
	v_pk_fma_f32 v[68:69], v[2:3], v[106:107], v[34:35]
	s_nop 0
	v_pk_fma_f32 v[68:69], v[10:11], v[126:127], v[68:69]
	s_nop 0
	v_pk_fma_f32 v[68:69], v[18:19], v[114:115], v[68:69]
	s_nop 0
	v_pk_fma_f32 v[106:107], v[26:27], v[104:105], v[68:69]
	s_and_saveexec_b64 s[28:29], s[6:7]
	s_xor_b64 s[76:77], exec, s[28:29]
	s_cbranch_execz .LBB0_198
	v_mul_f32_e32 v68, 0xbfb8aa3b, v178
	v_mul_f32_e32 v69, 0xbfb8aa3b, v179
	v_exp_f32_e32 v68, v68
	v_exp_f32_e32 v69, v69
	v_mul_f32_e32 v70, 0xbfb8aa3b, v176
	v_exp_f32_e32 v70, v70
	v_add_f32_e32 v68, 1.0, v68
	v_add_f32_e32 v69, 1.0, v69
	v_rcp_f32_e32 v68, v68
	v_rcp_f32_e32 v69, v69
	v_mul_f32_e32 v71, 0xbfb8aa3b, v177
	v_exp_f32_e32 v71, v71
	v_mul_f32_e32 v136, 0xbfb8aa3b, v175
	v_pk_mul_f32 v[68:69], v[178:179], v[68:69]
	v_exp_f32_e32 v136, v136
	v_cvt_pk_bf16_f32 v68, v68, v69
	v_add_f32_e32 v69, 1.0, v70
	v_rcp_f32_e32 v70, v69
	v_add_f32_e32 v69, 1.0, v71
	v_rcp_f32_e32 v71, v69
	v_mul_f32_e32 v69, 0xbfb8aa3b, v174
	v_exp_f32_e32 v69, v69
	v_mul_f32_e32 v165, 0xbfb8aa3b, v107
	v_pk_mul_f32 v[70:71], v[176:177], v[70:71]
	v_exp_f32_e32 v165, v165
	v_add_f32_e32 v69, 1.0, v69
	v_rcp_f32_e32 v176, v69
	v_add_f32_e32 v69, 1.0, v136
	v_mul_f32_e32 v136, 0xbfb8aa3b, v106
	v_exp_f32_e32 v136, v136
	v_rcp_f32_e32 v177, v69
	v_add_f32_e32 v69, 1.0, v136
	v_rcp_f32_e32 v178, v69
	v_add_f32_e32 v69, 1.0, v165
	v_rcp_f32_e32 v179, v69
	v_cvt_pk_bf16_f32 v69, v70, v71
	v_pk_mul_f32 v[70:71], v[174:175], v[176:177]
	v_pk_mul_f32 v[106:107], v[106:107], v[178:179]
	v_cvt_pk_bf16_f32 v70, v70, v71
	v_cvt_pk_bf16_f32 v71, v106, v107
	s_and_saveexec_b64 s[28:29], s[8:9]
	s_xor_b64 s[78:79], exec, s[28:29]
	s_cbranch_execz .LBB0_195
	v_add_u32_e32 v136, s88, v163
	v_lshl_add_u64 v[106:107], v[136:137], 1, s[52:53]
	v_add_u32_e32 v136, 8, v136
	global_store_dwordx2 v[106:107], v[68:69], off
	v_lshl_add_u64 v[106:107], v[136:137], 1, s[52:53]
	global_store_dwordx2 v[106:107], v[70:71], off
	s_and_saveexec_b64 s[80:81], s[10:11]
	v_add_u32_e32 v106, s90, v133
	ds_write_b128 v106, v[68:71]
	s_or_b64 exec, exec, s[80:81]

.LBB0_270:
	s_or_b64 exec, exec, s[76:77]
	v_add_u32_e32 v136, 0xfffe6200, v168
	v_lshl_add_u64 v[40:41], v[136:137], 1, s[26:27]
	v_add_u32_e32 v136, 0xfffe7400, v168
	v_lshl_add_u64 v[42:43], v[136:137], 1, s[26:27]
	v_add_u32_e32 v136, 0xfffe8600, v168
	global_load_dwordx4 v[68:71], v[40:41], off nt
	global_load_dwordx4 v[64:67], v[42:43], off nt
	v_lshl_add_u64 v[40:41], v[136:137], 1, s[26:27]
	v_add_u32_e32 v136, 0xfffe9800, v168
	v_lshl_add_u64 v[42:43], v[136:137], 1, s[26:27]
	v_add_u32_e32 v136, 0xfffeaa00, v168
	global_load_dwordx4 v[60:63], v[40:41], off nt
	global_load_dwordx4 v[56:59], v[42:43], off nt
	v_lshl_add_u64 v[40:41], v[136:137], 1, s[26:27]
	v_add_u32_e32 v136, 0xfffebc00, v168
	v_lshl_add_u64 v[42:43], v[136:137], 1, s[26:27]
	v_add_u32_e32 v136, 0xfffece00, v168
	global_load_dwordx4 v[52:55], v[40:41], off nt
	global_load_dwordx4 v[48:51], v[42:43], off nt
	v_lshl_add_u64 v[40:41], v[136:137], 1, s[26:27]
	v_add_u32_e32 v136, 0xfffee000, v168
	v_lshl_add_u64 v[42:43], v[136:137], 1, s[26:27]
	global_load_dwordx4 v[44:47], v[40:41], off nt
	s_nop 0
	global_load_dwordx4 v[40:43], v[42:43], off nt
	s_waitcnt vmcnt(15)
	v_lshlrev_b32_e32 v180, 16, v100
	v_and_b32_e32 v181, 0xffff0000, v100
	v_lshlrev_b32_e32 v178, 16, v101
	v_and_b32_e32 v179, 0xffff0000, v101
	v_pk_fma_f32 v[100:101], v[6:7], v[108:109], v[38:39]
	v_lshlrev_b32_e32 v176, 16, v102
	v_pk_fma_f32 v[100:101], v[14:15], v[124:125], v[100:101]
	v_and_b32_e32 v177, 0xffff0000, v102
	v_pk_fma_f32 v[100:101], v[22:23], v[116:117], v[100:101]
	v_pk_fma_f32 v[110:111], v[4:5], v[110:111], v[36:37]
	v_pk_fma_f32 v[108:109], v[30:31], v[178:179], v[100:101]
	v_pk_fma_f32 v[100:101], v[0:1], v[106:107], v[32:33]
	v_pk_fma_f32 v[110:111], v[12:13], v[126:127], v[110:111]
	v_pk_fma_f32 v[100:101], v[8:9], v[122:123], v[100:101]
	v_pk_fma_f32 v[110:111], v[20:21], v[118:119], v[110:111]
	v_pk_fma_f32 v[100:101], v[16:17], v[114:115], v[100:101]
	v_lshlrev_b32_e32 v174, 16, v103
	v_pk_fma_f32 v[106:107], v[24:25], v[176:177], v[100:101]
	v_pk_fma_f32 v[100:101], v[2:3], v[104:105], v[34:35]
	v_and_b32_e32 v175, 0xffff0000, v103
	v_pk_fma_f32 v[100:101], v[10:11], v[120:121], v[100:101]
	v_pk_fma_f32 v[110:111], v[28:29], v[180:181], v[110:111]
	v_pk_fma_f32 v[100:101], v[18:19], v[112:113], v[100:101]
	s_nop 0
	v_pk_fma_f32 v[104:105], v[26:27], v[174:175], v[100:101]
	s_and_saveexec_b64 s[28:29], s[6:7]
	s_xor_b64 s[76:77], exec, s[28:29]
	s_cbranch_execz .LBB0_278
	v_mul_f32_e32 v100, 0xbfb8aa3b, v110
	v_mul_f32_e32 v101, 0xbfb8aa3b, v111
	v_exp_f32_e32 v100, v100
	v_exp_f32_e32 v101, v101
	v_mul_f32_e32 v102, 0xbfb8aa3b, v108
	v_exp_f32_e32 v102, v102
	v_add_f32_e32 v100, 1.0, v100
	v_add_f32_e32 v101, 1.0, v101
	v_rcp_f32_e32 v100, v100
	v_rcp_f32_e32 v101, v101
	v_mul_f32_e32 v103, 0xbfb8aa3b, v109
	v_exp_f32_e32 v103, v103
	v_pk_mul_f32 v[100:101], v[110:111], v[100:101]
	s_nop 0
	v_cvt_pk_bf16_f32 v100, v100, v101
	v_add_f32_e32 v101, 1.0, v102
	v_rcp_f32_e32 v102, v101
	v_add_f32_e32 v101, 1.0, v103
	v_rcp_f32_e32 v103, v101
	v_mul_f32_e32 v101, 0xbfb8aa3b, v106
	v_exp_f32_e32 v101, v101
	v_mul_f32_e32 v110, 0xbfb8aa3b, v107
	v_exp_f32_e32 v110, v110
	v_pk_mul_f32 v[102:103], v[108:109], v[102:103]
	v_add_f32_e32 v101, 1.0, v101
	v_mul_f32_e32 v109, 0xbfb8aa3b, v104
	v_rcp_f32_e32 v108, v101
	v_add_f32_e32 v101, 1.0, v110
	v_exp_f32_e32 v110, v109
	v_mul_f32_e32 v109, 0xbfb8aa3b, v105
	v_exp_f32_e32 v111, v109
	v_rcp_f32_e32 v109, v101
	v_add_f32_e32 v101, 1.0, v110
	v_rcp_f32_e32 v110, v101
	v_add_f32_e32 v101, 1.0, v111
	v_rcp_f32_e32 v111, v101
	v_cvt_pk_bf16_f32 v101, v102, v103
	v_pk_mul_f32 v[102:103], v[106:107], v[108:109]
	v_pk_mul_f32 v[104:105], v[104:105], v[110:111]
	v_cvt_pk_bf16_f32 v102, v102, v103
	v_cvt_pk_bf16_f32 v103, v104, v105
	s_and_saveexec_b64 s[28:29], s[8:9]
	s_xor_b64 s[78:79], exec, s[28:29]
	s_cbranch_execz .LBB0_275
	v_add_u32_e32 v106, s88, v163
	v_add_u32_e32 v136, 0x1000, v106
	v_lshl_add_u64 v[104:105], v[136:137], 1, s[52:53]
	v_add_u32_e32 v136, 0x1008, v106
	global_store_dwordx2 v[104:105], v[100:101], off
	v_lshl_add_u64 v[104:105], v[136:137], 1, s[52:53]
	global_store_dwordx2 v[104:105], v[102:103], off
	s_and_saveexec_b64 s[80:81], s[10:11]
	v_add_u32_e32 v104, s90, v133
	ds_write_b128 v104, v[100:103] offset:4096
	s_or_b64 exec, exec, s[80:81]

.LBB0_350:
	s_or_b64 exec, exec, s[76:77]
	v_add_u32_e32 v136, 0xfffef200, v168
	v_lshl_add_u64 v[72:73], v[136:137], 1, s[26:27]
	v_add_u32_e32 v136, 0xffff0400, v168
	v_lshl_add_u64 v[74:75], v[136:137], 1, s[26:27]
	v_add_u32_e32 v136, 0xffff1600, v168
	global_load_dwordx4 v[100:103], v[72:73], off nt
	global_load_dwordx4 v[96:99], v[74:75], off nt
	v_lshl_add_u64 v[72:73], v[136:137], 1, s[26:27]
	v_add_u32_e32 v136, 0xffff2800, v168
	v_lshl_add_u64 v[74:75], v[136:137], 1, s[26:27]
	v_add_u32_e32 v136, 0xffff3a00, v168
	global_load_dwordx4 v[92:95], v[72:73], off nt
	global_load_dwordx4 v[88:91], v[74:75], off nt
	v_lshl_add_u64 v[72:73], v[136:137], 1, s[26:27]
	v_add_u32_e32 v136, 0xffff4c00, v168
	v_lshl_add_u64 v[74:75], v[136:137], 1, s[26:27]
	v_add_u32_e32 v136, 0xffff5e00, v168
	global_load_dwordx4 v[84:87], v[72:73], off nt
	global_load_dwordx4 v[80:83], v[74:75], off nt
	v_lshl_add_u64 v[72:73], v[136:137], 1, s[26:27]
	v_add_u32_e32 v136, 0xffff7000, v168
	v_lshl_add_u64 v[74:75], v[136:137], 1, s[26:27]
	global_load_dwordx4 v[76:79], v[72:73], off nt
	s_nop 0
	global_load_dwordx4 v[72:75], v[74:75], off nt
	v_pk_fma_f32 v[110:111], v[4:5], v[110:111], v[36:37]
	v_pk_fma_f32 v[108:109], v[6:7], v[108:109], v[38:39]
	v_pk_fma_f32 v[106:107], v[0:1], v[106:107], v[32:33]
	v_pk_fma_f32 v[104:105], v[2:3], v[104:105], v[34:35]
	v_pk_fma_f32 v[110:111], v[12:13], v[126:127], v[110:111]
	v_pk_fma_f32 v[108:109], v[14:15], v[124:125], v[108:109]
	v_pk_fma_f32 v[106:107], v[8:9], v[122:123], v[106:107]
	v_pk_fma_f32 v[104:105], v[10:11], v[120:121], v[104:105]
	s_waitcnt vmcnt(15)
	v_lshlrev_b32_e32 v192, 16, v68
	v_and_b32_e32 v193, 0xffff0000, v68
	v_pk_fma_f32 v[110:111], v[20:21], v[118:119], v[110:111]
	v_lshlrev_b32_e32 v190, 16, v69
	v_and_b32_e32 v191, 0xffff0000, v69
	v_pk_fma_f32 v[108:109], v[22:23], v[116:117], v[108:109]
	v_lshlrev_b32_e32 v188, 16, v70
	v_and_b32_e32 v189, 0xffff0000, v70
	v_pk_fma_f32 v[106:107], v[16:17], v[114:115], v[106:107]
	v_lshlrev_b32_e32 v186, 16, v71
	v_and_b32_e32 v187, 0xffff0000, v71
	v_pk_fma_f32 v[104:105], v[18:19], v[112:113], v[104:105]
	v_pk_fma_f32 v[172:173], v[28:29], v[192:193], v[110:111]
	v_pk_fma_f32 v[110:111], v[30:31], v[190:191], v[108:109]
	v_pk_fma_f32 v[106:107], v[24:25], v[188:189], v[106:107]
	v_pk_fma_f32 v[108:109], v[26:27], v[186:187], v[104:105]
	s_and_saveexec_b64 s[28:29], s[6:7]
	s_xor_b64 s[76:77], exec, s[28:29]
	s_cbranch_execz .LBB0_358
	v_mul_f32_e32 v104, 0xbfb8aa3b, v172
	v_mul_f32_e32 v105, 0xbfb8aa3b, v173
	v_exp_f32_e32 v104, v104
	v_exp_f32_e32 v105, v105
	v_mul_f32_e32 v136, 0xbfb8aa3b, v110
	v_exp_f32_e32 v136, v136
	v_add_f32_e32 v104, 1.0, v104
	v_add_f32_e32 v105, 1.0, v105
	v_rcp_f32_e32 v104, v104
	v_rcp_f32_e32 v105, v105
	v_mul_f32_e32 v165, 0xbfb8aa3b, v111
	v_exp_f32_e32 v165, v165
	v_pk_mul_f32 v[104:105], v[172:173], v[104:105]
	s_nop 0
	v_cvt_pk_bf16_f32 v104, v104, v105
	v_add_f32_e32 v105, 1.0, v136
	v_rcp_f32_e32 v172, v105
	v_add_f32_e32 v105, 1.0, v165
	v_rcp_f32_e32 v173, v105
	v_mul_f32_e32 v105, 0xbfb8aa3b, v106
	v_exp_f32_e32 v105, v105
	v_mul_f32_e32 v136, 0xbfb8aa3b, v107
	v_exp_f32_e32 v136, v136
	v_pk_mul_f32 v[110:111], v[110:111], v[172:173]
	v_add_f32_e32 v105, 1.0, v105
	v_rcp_f32_e32 v172, v105
	v_add_f32_e32 v105, 1.0, v136
	v_mul_f32_e32 v136, 0xbfb8aa3b, v108
	v_exp_f32_e32 v136, v136
	v_mul_f32_e32 v165, 0xbfb8aa3b, v109
	v_exp_f32_e32 v165, v165
	v_rcp_f32_e32 v173, v105
	v_add_f32_e32 v105, 1.0, v136
	v_rcp_f32_e32 v174, v105
	v_add_f32_e32 v105, 1.0, v165
	v_rcp_f32_e32 v175, v105
	v_pk_mul_f32 v[106:107], v[106:107], v[172:173]
	v_cvt_pk_bf16_f32 v105, v110, v111
	v_cvt_pk_bf16_f32 v106, v106, v107
	v_pk_mul_f32 v[108:109], v[108:109], v[174:175]
	s_nop 0
	v_cvt_pk_bf16_f32 v107, v108, v109
	s_and_saveexec_b64 s[28:29], s[8:9]
	s_xor_b64 s[78:79], exec, s[28:29]
	s_cbranch_execz .LBB0_355
	v_add_u32_e32 v110, s88, v163
	v_add_u32_e32 v136, 0x2000, v110
	v_lshl_add_u64 v[108:109], v[136:137], 1, s[52:53]
	v_add_u32_e32 v136, 0x2008, v110
	global_store_dwordx2 v[108:109], v[104:105], off
	v_lshl_add_u64 v[108:109], v[136:137], 1, s[52:53]
	global_store_dwordx2 v[108:109], v[106:107], off
	s_and_saveexec_b64 s[80:81], s[10:11]
	v_add_u32_e32 v108, s90, v133
	ds_write_b128 v108, v[104:107] offset:8192
	s_or_b64 exec, exec, s[80:81]

.LBB0_423:
	v_add_u32_e32 v136, 0xffff8200, v168
	v_lshl_add_u64 v[40:41], v[136:137], 1, s[26:27]
	v_add_u32_e32 v136, 0xffff9400, v168
	v_lshl_add_u64 v[42:43], v[136:137], 1, s[26:27]
	v_add_u32_e32 v136, 0xffffa600, v168
	global_load_dwordx4 v[68:71], v[40:41], off nt
	global_load_dwordx4 v[64:67], v[42:43], off nt
	v_lshl_add_u64 v[40:41], v[136:137], 1, s[26:27]
	v_add_u32_e32 v136, 0xffffb800, v168
	v_lshl_add_u64 v[42:43], v[136:137], 1, s[26:27]
	v_add_u32_e32 v136, 0xffffca00, v168
	global_load_dwordx4 v[60:63], v[40:41], off nt
	global_load_dwordx4 v[56:59], v[42:43], off nt
	v_lshl_add_u64 v[40:41], v[136:137], 1, s[26:27]
	v_add_u32_e32 v136, 0xffffdc00, v168
	v_lshl_add_u64 v[42:43], v[136:137], 1, s[26:27]
	v_add_u32_e32 v136, 0xffffee00, v168
	v_mov_b32_e32 v169, v137
	global_load_dwordx4 v[52:55], v[40:41], off nt
	global_load_dwordx4 v[48:51], v[42:43], off nt
	v_lshl_add_u64 v[40:41], v[136:137], 1, s[26:27]
	v_lshl_add_u64 v[42:43], v[168:169], 1, s[26:27]
	global_load_dwordx4 v[44:47], v[40:41], off nt
	s_nop 0
	global_load_dwordx4 v[40:43], v[42:43], off nt

.LBB0_620:
	v_add_co_u32_e32 v24, vcc, s99, v18
	s_movk_i32 s1, 0x1000
	s_nop 0
	v_addc_co_u32_e32 v25, vcc, 0, v19, vcc
	v_add_co_u32_e32 v94, vcc, s1, v18
	s_movk_i32 s3, 0x2000
	s_nop 0
	v_addc_co_u32_e32 v95, vcc, 0, v19, vcc
	v_add_co_u32_e32 v26, vcc, s3, v18
	v_lshl_add_u64 v[22:23], s[28:29], 0, v[20:21]
	s_add_u32 s0, s28, s66
	s_mov_b32 s5, 0x100000
	v_addc_co_u32_e32 v27, vcc, 0, v19, vcc
	s_mov_b32 s4, 0x358637bd
	s_addc_u32 s1, s29, s67
	v_add_co_u32_e32 v44, vcc, s5, v22
	s_mov_b32 s6, 0x101000
	v_mov_b64_e32 v[92:93], s[4:5]
	s_add_u32 s4, s0, 0x3c1d8000
	v_addc_co_u32_e32 v45, vcc, 0, v23, vcc
	v_add_co_u32_e32 v22, vcc, s6, v22
	s_addc_u32 s5, s1, 0
	global_load_dwordx4 v[28:31], v220, s[0:1]
	global_load_dwordx4 v[32:35], v220, s[0:1] offset:64
	global_load_dwordx4 v[36:39], v220, s[0:1] offset:128
	global_load_dwordx4 v[40:43], v220, s[0:1] offset:192
	global_load_dwordx2 v[96:97], v[44:45], off offset:512 nt
	global_load_dwordx2 v[98:99], v[44:45], off offset:1024 nt
	global_load_dwordx2 v[100:101], v[44:45], off offset:1536 nt
	global_load_dwordx2 v[102:103], v[44:45], off offset:2048 nt
	global_load_dwordx2 v[104:105], v[44:45], off offset:2560 nt
	global_load_dwordx2 v[106:107], v[44:45], off offset:3072 nt
	global_load_dwordx2 v[108:109], v[44:45], off offset:3584 nt
	v_addc_co_u32_e32 v23, vcc, 0, v23, vcc
	global_load_dwordx4 v[44:47], v0, s[4:5] offset:16
	global_load_dwordx4 v[48:51], v0, s[4:5] offset:32
	global_load_dwordx4 v[52:55], v0, s[4:5] offset:48
	global_load_dwordx2 v[110:111], v[22:23], off offset:-4096 nt
	global_load_dwordx2 v[112:113], v[22:23], off nt
	global_load_dwordx2 v[114:115], v[22:23], off offset:512 nt
	global_load_dwordx2 v[116:117], v[22:23], off offset:1024 nt
	global_load_dwordx2 v[118:119], v[22:23], off offset:1536 nt
	global_load_dwordx2 v[120:121], v[22:23], off offset:2048 nt
	global_load_dwordx2 v[122:123], v[22:23], off offset:2560 nt
	s_add_u32 s4, s0, 0x3c1d8040
	s_addc_u32 s5, s1, 0
	global_load_dwordx2 v[124:125], v[22:23], off offset:3072 nt
	s_nop 0
	global_load_dwordx2 v[22:23], v[22:23], off offset:3584 nt
	s_nop 0
	global_load_dwordx4 v[56:59], v0, s[4:5] offset:32
	global_load_dwordx4 v[60:63], v0, s[4:5] offset:48
	global_load_dwordx4 v[64:67], v0, s[4:5] offset:16
	s_add_u32 s4, s0, 0x3c1d8080
	s_addc_u32 s5, s1, 0
	global_load_dwordx4 v[68:71], v0, s[4:5] offset:48
	global_load_dwordx4 v[72:75], v0, s[4:5] offset:32
	global_load_dwordx4 v[76:79], v0, s[4:5] offset:16
	s_add_u32 s0, s0, 0x3c1d80c0
	s_addc_u32 s1, s1, 0
	global_load_dwordx4 v[80:83], v0, s[0:1] offset:32
	global_load_dwordx4 v[84:87], v0, s[0:1] offset:48
	global_load_dwordx4 v[88:91], v0, s[0:1] offset:16
	s_add_i32 s58, s58, s60
	s_add_u32 s66, s66, s68
	s_addc_u32 s67, s67, s69
	v_lshl_add_u64 v[20:21], v[20:21], 0, s[64:65]
	s_cmpk_lt_i32 s58, 0x4000
	s_waitcnt vmcnt(0)
	v_pk_add_f32 v[30:31], v[30:31], v[46:47]
	v_pk_add_f32 v[28:29], v[28:29], v[44:45]
	s_waitcnt vmcnt(18)
	v_pk_add_f32 v[44:45], v[50:51], v[54:55]
	v_pk_add_f32 v[46:47], v[48:49], v[52:53]
	v_pk_add_f32 v[30:31], v[30:31], v[44:45]
	v_pk_add_f32 v[28:29], v[28:29], v[46:47]
	v_mov_b32_e32 v45, v30
	v_mov_b32_e32 v44, v29
	v_mov_b32_e32 v29, v31
	v_pk_add_f32 v[28:29], v[44:45], v[28:29]
	s_waitcnt vmcnt(17)
	v_lshlrev_b32_e32 v48, 16, v110
	v_and_b32_e32 v49, 0xffff0000, v110
	s_waitcnt vmcnt(7)
	v_pk_add_f32 v[46:47], v[56:57], v[60:61]
	s_waitcnt vmcnt(6)
	v_pk_add_f32 v[30:31], v[34:35], v[66:67]
	v_pk_add_f32 v[32:33], v[32:33], v[64:65]
	v_pk_add_f32 v[34:35], v[58:59], v[62:63]
	v_pk_add_f32 v[32:33], v[32:33], v[46:47]
	v_pk_add_f32 v[30:31], v[30:31], v[34:35]
	v_mov_b32_e32 v34, v33
	v_mov_b32_e32 v35, v30
	v_mov_b32_e32 v33, v31
	s_waitcnt vmcnt(3)
	v_pk_add_f32 v[38:39], v[38:39], v[78:79]
	v_pk_add_f32 v[36:37], v[36:37], v[76:77]
	v_pk_add_f32 v[44:45], v[74:75], v[70:71]
	v_pk_add_f32 v[46:47], v[72:73], v[68:69]
	v_pk_add_f32 v[32:33], v[34:35], v[32:33]
	v_pk_add_f32 v[34:35], v[38:39], v[44:45]
	v_pk_add_f32 v[36:37], v[36:37], v[46:47]
	v_mov_b32_e32 v31, v28
	v_mov_b32_e32 v30, v32
	v_mov_b32_e32 v28, v33
	v_mov_b32_e32 v32, v37
	v_mov_b32_e32 v33, v34
	v_mov_b32_e32 v37, v35
	s_waitcnt vmcnt(0)
	v_pk_add_f32 v[34:35], v[42:43], v[90:91]
	v_pk_add_f32 v[38:39], v[40:41], v[88:89]
	v_pk_add_f32 v[40:41], v[82:83], v[86:87]
	v_pk_add_f32 v[42:43], v[80:81], v[84:85]
	v_pk_add_f32 v[28:29], v[30:31], v[28:29]
	v_pk_add_f32 v[30:31], v[32:33], v[36:37]
	v_pk_add_f32 v[32:33], v[34:35], v[40:41]
	v_pk_add_f32 v[34:35], v[38:39], v[42:43]
	v_pk_fma_f32 v[28:29], v[28:29], s[22:23], v[92:93] op_sel_hi:[1,0,0]
	v_mov_b32_e32 v36, v35
	v_mov_b32_e32 v37, v32
	v_mov_b32_e32 v35, v33
	v_mov_b32_e32 v33, v30
	v_mul_f32_e32 v30, 0x4b800000, v28
	v_cmp_gt_f32_e32 vcc, s98, v28
	v_pk_add_f32 v[34:35], v[36:37], v[34:35]
	v_mul_f32_e32 v1, 0x4b800000, v29
	v_cmp_gt_f32_e64 s[0:1], s98, v29
	v_cndmask_b32_e32 v28, v28, v30, vcc
	v_mov_b32_e32 v32, v34
	v_mov_b32_e32 v30, v35
	v_cndmask_b32_e64 v1, v29, v1, s[0:1]
	v_rsq_f32_e32 v34, v28
	v_pk_add_f32 v[28:29], v[32:33], v[30:31]
	v_rsq_f32_e32 v1, v1
	v_pk_fma_f32 v[28:29], v[28:29], s[22:23], v[92:93] op_sel_hi:[1,0,0]
	v_lshlrev_b32_e32 v50, 16, v111
	v_mul_f32_e32 v30, 0x4b800000, v29
	v_cmp_gt_f32_e64 s[6:7], s98, v29
	v_mul_f32_e32 v31, 0x4b800000, v28
	v_cmp_gt_f32_e64 s[4:5], s98, v28
	v_cndmask_b32_e64 v29, v29, v30, s[6:7]
	v_rsq_f32_e32 v64, v29
	v_cndmask_b32_e64 v28, v28, v31, s[4:5]
	v_mul_f32_e32 v30, 0x45800000, v1
	v_rsq_f32_e32 v65, v28
	v_and_b32_e32 v51, 0xffff0000, v111
	v_mul_f32_e32 v31, 0x45800000, v34
	v_cndmask_b32_e64 v28, v1, v30, s[0:1]
	v_lshlrev_b32_e32 v126, 16, v96
	v_and_b32_e32 v127, 0xffff0000, v96
	v_lshlrev_b32_e32 v96, 16, v97
	v_and_b32_e32 v97, 0xffff0000, v97
	v_lshlrev_b32_e32 v128, 16, v98
	v_and_b32_e32 v129, 0xffff0000, v98
	v_lshlrev_b32_e32 v98, 16, v99
	v_and_b32_e32 v99, 0xffff0000, v99
	v_lshlrev_b32_e32 v130, 16, v100
	v_and_b32_e32 v131, 0xffff0000, v100
	v_lshlrev_b32_e32 v100, 16, v101
	v_and_b32_e32 v101, 0xffff0000, v101
	v_lshlrev_b32_e32 v132, 16, v102
	v_and_b32_e32 v133, 0xffff0000, v102
	v_lshlrev_b32_e32 v102, 16, v103
	v_and_b32_e32 v103, 0xffff0000, v103
	v_lshlrev_b32_e32 v134, 16, v104
	v_and_b32_e32 v135, 0xffff0000, v104
	v_lshlrev_b32_e32 v104, 16, v105
	v_and_b32_e32 v105, 0xffff0000, v105
	v_lshlrev_b32_e32 v136, 16, v106
	v_and_b32_e32 v137, 0xffff0000, v106
	v_lshlrev_b32_e32 v106, 16, v107
	v_and_b32_e32 v107, 0xffff0000, v107
	v_lshlrev_b32_e32 v138, 16, v108
	v_and_b32_e32 v139, 0xffff0000, v108
	v_lshlrev_b32_e32 v108, 16, v109
	v_and_b32_e32 v109, 0xffff0000, v109
	v_cndmask_b32_e32 v30, v34, v31, vcc
	v_pk_mul_f32 v[32:33], v[28:29], v[48:49] op_sel_hi:[0,1]
	v_pk_mul_f32 v[34:35], v[28:29], v[50:51] op_sel_hi:[0,1]
	v_pk_mul_f32 v[36:37], v[28:29], v[126:127] op_sel_hi:[0,1]
	v_pk_mul_f32 v[38:39], v[28:29], v[96:97] op_sel_hi:[0,1]
	v_pk_mul_f32 v[40:41], v[28:29], v[128:129] op_sel_hi:[0,1]
	v_pk_mul_f32 v[42:43], v[28:29], v[98:99] op_sel_hi:[0,1]
	v_pk_mul_f32 v[44:45], v[28:29], v[130:131] op_sel_hi:[0,1]
	v_pk_mul_f32 v[46:47], v[28:29], v[100:101] op_sel_hi:[0,1]
	v_pk_mul_f32 v[48:49], v[30:31], v[132:133] op_sel_hi:[0,1]
	v_pk_mul_f32 v[50:51], v[30:31], v[102:103] op_sel_hi:[0,1]
	v_pk_mul_f32 v[52:53], v[30:31], v[134:135] op_sel_hi:[0,1]
	v_pk_mul_f32 v[54:55], v[30:31], v[104:105] op_sel_hi:[0,1]
	v_pk_mul_f32 v[56:57], v[30:31], v[136:137] op_sel_hi:[0,1]
	v_pk_mul_f32 v[58:59], v[30:31], v[106:107] op_sel_hi:[0,1]
	v_pk_mul_f32 v[60:61], v[30:31], v[138:139] op_sel_hi:[0,1]
	v_pk_mul_f32 v[62:63], v[30:31], v[108:109] op_sel_hi:[0,1]
	v_pk_mul_f32 v[30:31], v[4:5], v[34:35]
	v_pk_mul_f32 v[28:29], v[2:3], v[32:33]
	v_mul_f32_e32 v1, 0x45800000, v64
	v_lshlrev_b32_e32 v110, 16, v112
	v_and_b32_e32 v111, 0xffff0000, v112
	v_lshlrev_b32_e32 v112, 16, v113
	v_and_b32_e32 v113, 0xffff0000, v113
	v_pk_mul_f32 v[34:35], v[8:9], v[38:39]
	v_pk_mul_f32 v[32:33], v[6:7], v[36:37]
	v_pk_mul_f32 v[38:39], v[12:13], v[42:43]
	v_pk_mul_f32 v[36:37], v[10:11], v[40:41]
	v_pk_mul_f32 v[42:43], v[16:17], v[46:47]
	v_pk_mul_f32 v[40:41], v[14:15], v[44:45]
	v_pk_mul_f32 v[46:47], v[4:5], v[50:51]
	v_pk_mul_f32 v[44:45], v[2:3], v[48:49]
	v_pk_mul_f32 v[50:51], v[8:9], v[54:55]
	v_pk_mul_f32 v[48:49], v[6:7], v[52:53]
	v_pk_mul_f32 v[54:55], v[12:13], v[58:59]
	v_pk_mul_f32 v[52:53], v[10:11], v[56:57]
	v_pk_mul_f32 v[58:59], v[16:17], v[62:63]
	v_pk_mul_f32 v[56:57], v[14:15], v[60:61]
	global_store_dwordx4 v[18:19], v[28:31], off nt
	global_store_dwordx4 v[18:19], v[32:35], off offset:1024 nt
	global_store_dwordx4 v[18:19], v[36:39], off offset:2048 nt
	global_store_dwordx4 v[18:19], v[40:43], off offset:3072 nt
	global_store_dwordx4 v[26:27], v[44:47], off offset:-4096 nt
	global_store_dwordx4 v[94:95], v[48:51], off offset:1024 nt
	global_store_dwordx4 v[94:95], v[52:55], off offset:2048 nt
	global_store_dwordx4 v[94:95], v[56:59], off offset:3072 nt
	v_mul_f32_e32 v29, 0x45800000, v65
	v_cndmask_b32_e64 v28, v64, v1, s[6:7]
	v_lshlrev_b32_e32 v140, 16, v114
	v_and_b32_e32 v141, 0xffff0000, v114
	v_lshlrev_b32_e32 v114, 16, v115
	v_and_b32_e32 v115, 0xffff0000, v115
	v_lshlrev_b32_e32 v142, 16, v116
	v_and_b32_e32 v143, 0xffff0000, v116
	v_lshlrev_b32_e32 v116, 16, v117
	v_and_b32_e32 v117, 0xffff0000, v117
	v_lshlrev_b32_e32 v144, 16, v118
	v_and_b32_e32 v145, 0xffff0000, v118
	v_lshlrev_b32_e32 v118, 16, v119
	v_and_b32_e32 v119, 0xffff0000, v119
	v_lshlrev_b32_e32 v146, 16, v120
	v_and_b32_e32 v147, 0xffff0000, v120
	v_lshlrev_b32_e32 v120, 16, v121
	v_and_b32_e32 v121, 0xffff0000, v121
	v_lshlrev_b32_e32 v148, 16, v122
	v_and_b32_e32 v149, 0xffff0000, v122
	v_lshlrev_b32_e32 v122, 16, v123
	v_and_b32_e32 v123, 0xffff0000, v123
	v_lshlrev_b32_e32 v150, 16, v124
	v_and_b32_e32 v151, 0xffff0000, v124
	v_lshlrev_b32_e32 v124, 16, v125
	v_and_b32_e32 v125, 0xffff0000, v125
	v_lshlrev_b32_e32 v152, 16, v22
	v_and_b32_e32 v153, 0xffff0000, v22
	v_lshlrev_b32_e32 v22, 16, v23
	v_and_b32_e32 v23, 0xffff0000, v23
	v_cndmask_b32_e64 v30, v65, v29, s[4:5]
	v_pk_mul_f32 v[32:33], v[28:29], v[110:111] op_sel_hi:[0,1]
	v_pk_mul_f32 v[34:35], v[28:29], v[112:113] op_sel_hi:[0,1]
	v_lshl_add_u64 v[18:19], v[18:19], 0, s[62:63]
	v_pk_mul_f32 v[36:37], v[28:29], v[140:141] op_sel_hi:[0,1]
	v_pk_mul_f32 v[38:39], v[28:29], v[114:115] op_sel_hi:[0,1]
	v_pk_mul_f32 v[40:41], v[28:29], v[142:143] op_sel_hi:[0,1]
	v_pk_mul_f32 v[42:43], v[28:29], v[116:117] op_sel_hi:[0,1]
	v_pk_mul_f32 v[44:45], v[28:29], v[144:145] op_sel_hi:[0,1]
	v_pk_mul_f32 v[46:47], v[28:29], v[118:119] op_sel_hi:[0,1]
	v_pk_mul_f32 v[48:49], v[30:31], v[146:147] op_sel_hi:[0,1]
	v_pk_mul_f32 v[50:51], v[30:31], v[120:121] op_sel_hi:[0,1]
	v_pk_mul_f32 v[52:53], v[30:31], v[148:149] op_sel_hi:[0,1]
	v_pk_mul_f32 v[54:55], v[30:31], v[122:123] op_sel_hi:[0,1]
	v_pk_mul_f32 v[56:57], v[30:31], v[150:151] op_sel_hi:[0,1]
	v_pk_mul_f32 v[58:59], v[30:31], v[124:125] op_sel_hi:[0,1]
	v_pk_mul_f32 v[60:61], v[30:31], v[152:153] op_sel_hi:[0,1]
	v_pk_mul_f32 v[22:23], v[30:31], v[22:23] op_sel_hi:[0,1]
	v_pk_mul_f32 v[30:31], v[4:5], v[34:35]
	v_pk_mul_f32 v[28:29], v[2:3], v[32:33]
	v_pk_mul_f32 v[34:35], v[8:9], v[38:39]
	v_pk_mul_f32 v[32:33], v[6:7], v[36:37]
	v_pk_mul_f32 v[38:39], v[12:13], v[42:43]
	v_pk_mul_f32 v[36:37], v[10:11], v[40:41]
	v_pk_mul_f32 v[42:43], v[16:17], v[46:47]
	v_pk_mul_f32 v[40:41], v[14:15], v[44:45]
	v_pk_mul_f32 v[46:47], v[4:5], v[50:51]
	v_pk_mul_f32 v[44:45], v[2:3], v[48:49]
	v_pk_mul_f32 v[50:51], v[8:9], v[54:55]
	v_pk_mul_f32 v[48:49], v[6:7], v[52:53]
	v_pk_mul_f32 v[54:55], v[12:13], v[58:59]
	v_pk_mul_f32 v[52:53], v[10:11], v[56:57]
	v_pk_mul_f32 v[58:59], v[16:17], v[22:23]
	v_pk_mul_f32 v[56:57], v[14:15], v[60:61]
	global_store_dwordx4 v[26:27], v[28:31], off nt
	global_store_dwordx4 v[26:27], v[32:35], off offset:1024 nt
	global_store_dwordx4 v[26:27], v[36:39], off offset:2048 nt
	global_store_dwordx4 v[26:27], v[40:43], off offset:3072 nt
	global_store_dwordx4 v[24:25], v[44:47], off nt
	global_store_dwordx4 v[24:25], v[48:51], off offset:1024 nt
	global_store_dwordx4 v[24:25], v[52:55], off offset:2048 nt
	global_store_dwordx4 v[24:25], v[56:59], off offset:3072 nt
	s_cbranch_scc1 .LBB0_620
